# qn / qr stores of the in-projection epilogue non-temporal (64 MiB consumed later by non-temporal loads)
# baseline (speedup 1.0000x reference)
;     __device__ __forceinline__ void operator()(const f32x4 (&acc)[2][2][4][2], const pg8::Unit& u, int wr, int wc, int fr, int fq) const {
;     ...
;                         bf16_t* p = qn + (size_t)row * 512 + cs * 64 + d0; store8(p, y); store8(p + 32, y + 8);
;                         bf16_t* p2 = qr + (size_t)row * 512 + cs * 64 + d0; store8(p2, r1); store8(p2 + 32, r2);
.LBB0_192:
	s_andn2_b64 vcc, exec, s[6:7]
	s_cbranch_vccnz .LBB0_194
	v_ashrrev_i32_e32 v121, 31, v120
	v_lshlrev_b64 v[168:169], 10, v[120:121]
	v_lshl_add_u64 v[208:209], s[16:17], 0, v[168:169]
	s_lshl_b64 s[6:7], s[94:95], 1
	v_lshl_add_u64 v[208:209], v[208:209], 0, s[6:7]
	v_lshlrev_b32_e32 v136, 1, v140
	v_lshl_add_u64 v[212:213], v[208:209], 0, v[136:137]
	v_cvt_pk_bf16_f32 v208, v171, v175
	v_cvt_pk_bf16_f32 v209, v126, v173
	v_cvt_pk_bf16_f32 v210, v124, v127
	v_cvt_pk_bf16_f32 v211, v122, v125
	global_store_dwordx4 v[212:213], v[208:211], off nt
	v_cvt_pk_bf16_f32 v124, v117, v119
	v_cvt_pk_bf16_f32 v125, v115, v118
	v_cvt_pk_bf16_f32 v126, v114, v116
	v_lshl_add_u64 v[114:115], s[18:19], 0, v[168:169]
	v_lshl_add_u64 v[114:115], v[114:115], 0, s[6:7]
	v_cvt_pk_bf16_f32 v127, v113, v185
	global_store_dwordx4 v[212:213], v[124:127], off offset:64 nt
	v_lshl_add_u64 v[118:119], v[114:115], 0, v[136:137]
	v_cvt_pk_bf16_f32 v114, v123, v189
	v_cvt_pk_bf16_f32 v115, v193, v197
	v_cvt_pk_bf16_f32 v116, v200, v202
	v_cvt_pk_bf16_f32 v117, v205, v206
	global_store_dwordx4 v[118:119], v[114:117], off nt
	v_cvt_pk_bf16_f32 v112, v112, v187
	v_cvt_pk_bf16_f32 v113, v191, v195
	s_nop 1
	v_cvt_pk_bf16_f32 v114, v199, v201
	v_cvt_pk_bf16_f32 v115, v203, v204
	global_store_dwordx4 v[118:119], v[112:115], off offset:64 nt

;     __device__ __forceinline__ void operator()(const f32x4 (&acc)[2][2][4][2], const pg8::Unit& u, int wr, int wc, int fr, int fq) const {
;     ...
;                         bf16_t* p = qn + (size_t)row * 512 + cs * 64 + d0; store8(p, y); store8(p + 32, y + 8);
;                         bf16_t* p2 = qr + (size_t)row * 512 + cs * 64 + d0; store8(p2, r1); store8(p2 + 32, r2);
.LBB0_225:
	s_andn2_b64 vcc, exec, s[54:55]
	s_cbranch_vccnz .LBB0_227
	v_ashrrev_i32_e32 v105, 31, v104
	v_lshlrev_b64 v[104:105], 10, v[104:105]
	v_lshl_add_u64 v[198:199], s[16:17], 0, v[104:105]
	s_lshl_b64 s[54:55], s[94:95], 1
	v_lshl_add_u64 v[198:199], v[198:199], 0, s[54:55]
	v_lshlrev_b32_e32 v136, 1, v140
	v_lshl_add_u64 v[202:203], v[198:199], 0, v[136:137]
	v_cvt_pk_bf16_f32 v198, v112, v114
	v_cvt_pk_bf16_f32 v199, v110, v113
	v_cvt_pk_bf16_f32 v200, v108, v111
	v_cvt_pk_bf16_f32 v201, v106, v109
	global_store_dwordx4 v[202:203], v[198:201], off nt
	v_cvt_pk_bf16_f32 v108, v101, v103
	v_cvt_pk_bf16_f32 v109, v99, v102
	v_cvt_pk_bf16_f32 v110, v98, v100
	v_lshl_add_u64 v[98:99], s[18:19], 0, v[104:105]
	v_lshl_add_u64 v[98:99], v[98:99], 0, s[54:55]
	v_cvt_pk_bf16_f32 v111, v97, v115
	global_store_dwordx4 v[202:203], v[108:111], off offset:64 nt
	v_lshl_add_u64 v[102:103], v[98:99], 0, v[136:137]
	v_cvt_pk_bf16_f32 v98, v107, v117
	v_cvt_pk_bf16_f32 v99, v119, v123
	v_cvt_pk_bf16_f32 v100, v125, v127
	v_cvt_pk_bf16_f32 v101, v173, v175
	global_store_dwordx4 v[102:103], v[98:101], off nt
	v_cvt_pk_bf16_f32 v96, v96, v116
	v_cvt_pk_bf16_f32 v97, v118, v122
	s_nop 1
	v_cvt_pk_bf16_f32 v98, v124, v126
	v_cvt_pk_bf16_f32 v99, v169, v171
	global_store_dwordx4 v[102:103], v[96:99], off offset:64 nt

;     __device__ __forceinline__ void operator()(const f32x4 (&acc)[2][2][4][2], const pg8::Unit& u, int wr, int wc, int fr, int fq) const {
;     ...
;                         bf16_t* p = qn + (size_t)row * 512 + cs * 64 + d0; store8(p, y); store8(p + 32, y + 8);
;                         bf16_t* p2 = qr + (size_t)row * 512 + cs * 64 + d0; store8(p2, r1); store8(p2 + 32, r2);
.LBB0_258:
	s_andn2_b64 vcc, exec, s[54:55]
	s_cbranch_vccnz .LBB0_260
	v_ashrrev_i32_e32 v89, 31, v88
	v_lshlrev_b64 v[88:89], 10, v[88:89]
	v_lshl_add_u64 v[116:117], s[16:17], 0, v[88:89]
	s_lshl_b64 s[54:55], s[94:95], 1
	v_lshl_add_u64 v[116:117], v[116:117], 0, s[54:55]
	v_lshlrev_b32_e32 v136, 1, v140
	v_lshl_add_u64 v[122:123], v[116:117], 0, v[136:137]
	v_cvt_pk_bf16_f32 v116, v96, v98
	v_cvt_pk_bf16_f32 v117, v94, v97
	v_cvt_pk_bf16_f32 v118, v92, v95
	v_cvt_pk_bf16_f32 v119, v90, v93
	global_store_dwordx4 v[122:123], v[116:119], off nt
	v_cvt_pk_bf16_f32 v92, v85, v87
	v_cvt_pk_bf16_f32 v93, v83, v86
	v_cvt_pk_bf16_f32 v94, v82, v84
	v_lshl_add_u64 v[82:83], s[18:19], 0, v[88:89]
	v_lshl_add_u64 v[82:83], v[82:83], 0, s[54:55]
	v_cvt_pk_bf16_f32 v95, v81, v99
	global_store_dwordx4 v[122:123], v[92:95], off offset:64 nt
	v_lshl_add_u64 v[86:87], v[82:83], 0, v[136:137]
	v_cvt_pk_bf16_f32 v82, v91, v101
	v_cvt_pk_bf16_f32 v83, v103, v105
	v_cvt_pk_bf16_f32 v84, v107, v110
	v_cvt_pk_bf16_f32 v85, v113, v114
	global_store_dwordx4 v[86:87], v[82:85], off nt
	v_cvt_pk_bf16_f32 v80, v80, v100
	v_cvt_pk_bf16_f32 v81, v102, v104
	s_nop 1
	v_cvt_pk_bf16_f32 v82, v106, v109
	v_cvt_pk_bf16_f32 v83, v111, v112
	global_store_dwordx4 v[86:87], v[80:83], off offset:64 nt

;     __device__ __forceinline__ void operator()(const f32x4 (&acc)[2][2][4][2], const pg8::Unit& u, int wr, int wc, int fr, int fq) const {
;     ...
;                         bf16_t* p = qn + (size_t)row * 512 + cs * 64 + d0; store8(p, y); store8(p + 32, y + 8);
;                         bf16_t* p2 = qr + (size_t)row * 512 + cs * 64 + d0; store8(p2, r1); store8(p2 + 32, r2);
.LBB0_291:
	s_andn2_b64 vcc, exec, s[54:55]
	s_cbranch_vccnz .LBB0_293
	v_ashrrev_i32_e32 v81, 31, v80
	v_lshlrev_b64 v[80:81], 10, v[80:81]
	v_lshl_add_u64 v[100:101], s[16:17], 0, v[80:81]
	s_lshl_b64 s[52:53], s[94:95], 1
	v_lshl_add_u64 v[100:101], v[100:101], 0, s[52:53]
	v_lshlrev_b32_e32 v136, 1, v140
	v_lshl_add_u64 v[104:105], v[100:101], 0, v[136:137]
	v_cvt_pk_bf16_f32 v100, v85, v87
	v_cvt_pk_bf16_f32 v101, v82, v86
	v_cvt_pk_bf16_f32 v102, v74, v84
	v_cvt_pk_bf16_f32 v103, v73, v75
	global_store_dwordx4 v[104:105], v[100:103], off nt
	v_cvt_pk_bf16_f32 v70, v70, v72
	v_cvt_pk_bf16_f32 v71, v69, v71
	v_cvt_pk_bf16_f32 v72, v68, v65
	v_cvt_pk_bf16_f32 v73, v64, v67
	v_lshl_add_u64 v[64:65], s[18:19], 0, v[80:81]
	v_lshl_add_u64 v[64:65], v[64:65], 0, s[52:53]
	global_store_dwordx4 v[104:105], v[70:73], off offset:64 nt
	v_cvt_pk_bf16_f32 v68, v76, v78
	v_cvt_pk_bf16_f32 v69, v83, v89
	s_nop 1
	v_lshl_add_u64 v[72:73], v[64:65], 0, v[136:137]
	v_cvt_pk_bf16_f32 v70, v91, v94
	v_cvt_pk_bf16_f32 v71, v95, v98
	global_store_dwordx4 v[72:73], v[68:71], off nt
	v_cvt_pk_bf16_f32 v64, v66, v77
	v_cvt_pk_bf16_f32 v65, v79, v88
	v_cvt_pk_bf16_f32 v66, v90, v93
	v_cvt_pk_bf16_f32 v67, v96, v97
	global_store_dwordx4 v[72:73], v[64:67], off offset:64 nt

;     __device__ __forceinline__ void operator()(const f32x4 (&acc)[2][2][4][2], const pg8::Unit& u, int wr, int wc, int fr, int fq) const {
;     ...
;                         bf16_t* p = qn + (size_t)row * 512 + cs * 64 + d0; store8(p, y); store8(p + 32, y + 8);
;                         bf16_t* p2 = qr + (size_t)row * 512 + cs * 64 + d0; store8(p2, r1); store8(p2 + 32, r2);
.LBB0_324:
	s_andn2_b64 vcc, exec, s[54:55]
	s_cbranch_vccnz .LBB0_326
	v_ashrrev_i32_e32 v57, 31, v56
	v_lshlrev_b64 v[88:89], 10, v[56:57]
	v_lshl_add_u64 v[84:85], s[16:17], 0, v[88:89]
	s_lshl_b64 s[54:55], s[94:95], 1
	v_lshl_add_u64 v[84:85], v[84:85], 0, s[54:55]
	v_lshlrev_b32_e32 v136, 1, v140
	v_lshl_add_u64 v[90:91], v[84:85], 0, v[136:137]
	v_cvt_pk_bf16_f32 v84, v64, v66
	v_cvt_pk_bf16_f32 v85, v62, v65
	v_cvt_pk_bf16_f32 v86, v60, v63
	v_cvt_pk_bf16_f32 v87, v58, v61
	global_store_dwordx4 v[90:91], v[84:87], off nt
	v_cvt_pk_bf16_f32 v60, v53, v55
	v_cvt_pk_bf16_f32 v61, v51, v54
	v_cvt_pk_bf16_f32 v62, v50, v52
	v_lshl_add_u64 v[50:51], s[18:19], 0, v[88:89]
	v_lshl_add_u64 v[50:51], v[50:51], 0, s[54:55]
	v_cvt_pk_bf16_f32 v63, v49, v67
	global_store_dwordx4 v[90:91], v[60:63], off offset:64 nt
	v_lshl_add_u64 v[54:55], v[50:51], 0, v[136:137]
	v_cvt_pk_bf16_f32 v50, v59, v69
	v_cvt_pk_bf16_f32 v51, v71, v73
	v_cvt_pk_bf16_f32 v52, v75, v78
	v_cvt_pk_bf16_f32 v53, v81, v82
	global_store_dwordx4 v[54:55], v[50:53], off nt
	v_cvt_pk_bf16_f32 v48, v48, v68
	v_cvt_pk_bf16_f32 v49, v70, v72
	s_nop 1
	v_cvt_pk_bf16_f32 v50, v74, v77
	v_cvt_pk_bf16_f32 v51, v79, v80
	global_store_dwordx4 v[54:55], v[48:51], off offset:64 nt

;     __device__ __forceinline__ void operator()(const f32x4 (&acc)[2][2][4][2], const pg8::Unit& u, int wr, int wc, int fr, int fq) const {
;     ...
;                         bf16_t* p = qn + (size_t)row * 512 + cs * 64 + d0; store8(p, y); store8(p + 32, y + 8);
;                         bf16_t* p2 = qr + (size_t)row * 512 + cs * 64 + d0; store8(p2, r1); store8(p2 + 32, r2);
.LBB0_357:
	s_andn2_b64 vcc, exec, s[54:55]
	s_cbranch_vccnz .LBB0_359
	v_ashrrev_i32_e32 v41, 31, v40
	v_lshlrev_b64 v[40:41], 10, v[40:41]
	v_lshl_add_u64 v[68:69], s[16:17], 0, v[40:41]
	s_lshl_b64 s[54:55], s[94:95], 1
	v_lshl_add_u64 v[68:69], v[68:69], 0, s[54:55]
	v_lshlrev_b32_e32 v136, 1, v140
	v_lshl_add_u64 v[68:69], v[68:69], 0, v[136:137]
	v_cvt_pk_bf16_f32 v32, v32, v34
	v_cvt_pk_bf16_f32 v33, v33, v36
	v_cvt_pk_bf16_f32 v34, v35, v38
	v_cvt_pk_bf16_f32 v35, v37, v39
	global_store_dwordx4 v[68:69], v[32:35], off nt
	s_nop 1
	v_cvt_pk_bf16_f32 v32, v48, v49
	v_cvt_pk_bf16_f32 v33, v46, v47
	v_cvt_pk_bf16_f32 v34, v44, v45
	v_cvt_pk_bf16_f32 v35, v42, v43
	global_store_dwordx4 v[68:69], v[32:35], off offset:64 nt
	s_nop 1
	v_lshl_add_u64 v[32:33], s[18:19], 0, v[40:41]
	v_lshl_add_u64 v[32:33], v[32:33], 0, s[54:55]
	v_lshl_add_u64 v[36:37], v[32:33], 0, v[136:137]
	v_cvt_pk_bf16_f32 v32, v51, v53
	v_cvt_pk_bf16_f32 v33, v55, v59
	v_cvt_pk_bf16_f32 v34, v61, v63
	v_cvt_pk_bf16_f32 v35, v65, v67
	global_store_dwordx4 v[36:37], v[32:35], off nt
	s_nop 1
	v_cvt_pk_bf16_f32 v32, v50, v52
	v_cvt_pk_bf16_f32 v33, v54, v58
	v_cvt_pk_bf16_f32 v34, v60, v62
	v_cvt_pk_bf16_f32 v35, v64, v66
	global_store_dwordx4 v[36:37], v[32:35], off offset:64 nt

;     __device__ __forceinline__ void operator()(const f32x4 (&acc)[2][2][4][2], const pg8::Unit& u, int wr, int wc, int fr, int fq) const {
;     ...
;                         bf16_t* p = qn + (size_t)row * 512 + cs * 64 + d0; store8(p, y); store8(p + 32, y + 8);
;                         bf16_t* p2 = qr + (size_t)row * 512 + cs * 64 + d0; store8(p2, r1); store8(p2 + 32, r2);
.LBB0_390:
	s_andn2_b64 vcc, exec, s[54:55]
	s_cbranch_vccnz .LBB0_392
	v_ashrrev_i32_e32 v25, 31, v24
	v_lshlrev_b64 v[24:25], 10, v[24:25]
	v_lshl_add_u64 v[52:53], s[16:17], 0, v[24:25]
	s_lshl_b64 s[54:55], s[94:95], 1
	v_lshl_add_u64 v[52:53], v[52:53], 0, s[54:55]
	v_lshlrev_b32_e32 v136, 1, v140
	v_lshl_add_u64 v[58:59], v[52:53], 0, v[136:137]
	v_cvt_pk_bf16_f32 v52, v32, v34
	v_cvt_pk_bf16_f32 v53, v30, v33
	v_cvt_pk_bf16_f32 v54, v28, v31
	v_cvt_pk_bf16_f32 v55, v26, v29
	global_store_dwordx4 v[58:59], v[52:55], off nt
	v_cvt_pk_bf16_f32 v28, v21, v23
	v_cvt_pk_bf16_f32 v29, v19, v22
	v_cvt_pk_bf16_f32 v30, v18, v20
	v_lshl_add_u64 v[18:19], s[18:19], 0, v[24:25]
	v_lshl_add_u64 v[18:19], v[18:19], 0, s[54:55]
	v_cvt_pk_bf16_f32 v31, v17, v35
	global_store_dwordx4 v[58:59], v[28:31], off offset:64 nt
	v_lshl_add_u64 v[22:23], v[18:19], 0, v[136:137]
	v_cvt_pk_bf16_f32 v18, v27, v37
	v_cvt_pk_bf16_f32 v19, v39, v41
	v_cvt_pk_bf16_f32 v20, v43, v46
	v_cvt_pk_bf16_f32 v21, v49, v50
	global_store_dwordx4 v[22:23], v[18:21], off nt
	v_cvt_pk_bf16_f32 v16, v16, v36
	v_cvt_pk_bf16_f32 v17, v38, v40
	s_nop 1
	v_cvt_pk_bf16_f32 v18, v42, v45
	v_cvt_pk_bf16_f32 v19, v47, v48
	global_store_dwordx4 v[22:23], v[16:19], off offset:64 nt

;     __device__ __forceinline__ void operator()(const f32x4 (&acc)[2][2][4][2], const pg8::Unit& u, int wr, int wc, int fr, int fq) const {
;     ...
;                         bf16_t* p = qn + (size_t)row * 512 + cs * 64 + d0; store8(p, y); store8(p + 32, y + 8);
;                         bf16_t* p2 = qr + (size_t)row * 512 + cs * 64 + d0; store8(p2, r1); store8(p2 + 32, r2);
.LBB0_423:
	s_andn2_b64 vcc, exec, s[40:41]
	s_cbranch_vccnz .LBB0_425
	v_ashrrev_i32_e32 v9, 31, v8
	v_lshlrev_b64 v[8:9], 10, v[8:9]
	v_lshl_add_u64 v[38:39], s[16:17], 0, v[8:9]
	s_lshl_b64 s[6:7], s[94:95], 1
	v_lshl_add_u64 v[38:39], v[38:39], 0, s[6:7]
	v_mov_b32_e32 v1, v137
	v_lshl_add_u64 v[38:39], v[38:39], 0, v[0:1]
	v_cvt_pk_bf16_f32 v2, v2, v4
	v_cvt_pk_bf16_f32 v3, v3, v6
	v_cvt_pk_bf16_f32 v4, v5, v18
	v_cvt_pk_bf16_f32 v5, v7, v19
	global_store_dwordx4 v[38:39], v[2:5], off nt
	s_nop 1
	v_cvt_pk_bf16_f32 v2, v16, v17
	v_cvt_pk_bf16_f32 v3, v14, v15
	v_cvt_pk_bf16_f32 v4, v12, v13
	v_cvt_pk_bf16_f32 v5, v10, v11
	global_store_dwordx4 v[38:39], v[2:5], off offset:64 nt
	s_nop 1
	v_lshl_add_u64 v[2:3], s[18:19], 0, v[8:9]
	v_lshl_add_u64 v[2:3], v[2:3], 0, s[6:7]
	v_lshl_add_u64 v[4:5], v[2:3], 0, v[0:1]
	v_cvt_pk_bf16_f32 v0, v21, v23
	v_cvt_pk_bf16_f32 v1, v25, v27
	v_cvt_pk_bf16_f32 v2, v30, v32
	v_cvt_pk_bf16_f32 v3, v34, v36
	global_store_dwordx4 v[4:5], v[0:3], off nt
	s_nop 1
	v_cvt_pk_bf16_f32 v0, v20, v22
	v_cvt_pk_bf16_f32 v1, v24, v26
	v_cvt_pk_bf16_f32 v2, v29, v31
	v_cvt_pk_bf16_f32 v3, v33, v35
	global_store_dwordx4 v[4:5], v[0:3], off offset:64 nt
